# dn_scan: operand tiles prefetched two steps ahead (two register sets, step loop unrolled by 2)
# speedup vs baseline: 1.0048x; 1.0048x over previous
.LBB0_1370:
	s_or_b64 exec, exec, s[0:1]
	s_waitcnt lgkmcnt(0)
	v_mov_b32_e32 v0, v131
	s_barrier
	v_readlane_b32 s0, v251, 35
	v_ashrrev_i32_e32 v0, 8, v0
	s_nop 0
	v_add_u32_e32 v0, s0, v0
	s_nop 0
	v_readfirstlane_b32 s12, v0
	s_branch .LBB0_1372
.LBB0_1372:
	s_cmpk_gt_i32 s12, 0xff
	s_cbranch_scc1 .LBB0_1396
	s_ashr_i32 s8, s12, 2
	s_ashr_i32 s16, s12, 5
	s_and_b32 s0, s12, 4
	s_bfe_i32 s1, s12, 0x10002
	s_cmp_eq_u32 s0, 0
	s_cselect_b64 s[2:3], -1, 0
	s_lshl_b32 s14, s16, 8
	s_and_b32 s0, s1, 0xc0
	s_add_i32 s14, s14, 0x8000
	s_or_b32 s15, s14, s0
	s_mul_i32 s13, s8, 0x88000
	s_mul_hi_i32 s17, s8, 0x88000
	s_add_u32 s4, s52, s13
	v_mov_b32_e32 v39, v131
	s_addc_u32 s5, s53, s17
	s_add_u32 s6, s56, s13
	v_and_b32_e32 v43, 63, v39
	v_bitop3_b32 v0, v39, 63, v39 bitop3:0xc
	s_addc_u32 s7, s57, s17
	s_lshl_b32 s0, s12, 3
	v_readlane_b32 s10, v254, 23
	v_cndmask_b32_e64 v88, v0, v43, s[2:3]
	v_and_b32_e32 v42, 0xff, v39
	s_and_b32 s0, s0, 0xc0
	v_readlane_b32 s11, v254, 24
	v_or_b32_e32 v2, s15, v88
	v_mov_b64_e32 v[0:1], s[48:49]
	s_movk_i32 s9, 0x600
	s_mov_b32 s21, s11
	s_lshl_b32 s20, s0, 1
	v_lshlrev_b32_e32 v36, 3, v42
	v_mad_i64_i32 v[0:1], s[10:11], v2, s9, v[0:1]
	v_lshlrev_b32_e32 v2, 4, v42
	v_bfe_u32 v44, v39, 3, 5
	s_add_u32 s0, s48, s20
	v_and_b32_e32 v49, 56, v36
	global_load_dwordx4 v[4:7], v2, s[4:5]
	global_load_dwordx4 v[8:11], v2, s[6:7]
	v_xor_b32_e32 v2, 63, v44
	s_addc_u32 s1, s49, 0
	v_lshlrev_b32_e32 v128, 1, v49
	v_cndmask_b32_e64 v90, v2, v44, s[2:3]
	v_and_b32_e32 v45, 24, v44
	v_lshl_add_u64 v[62:63], s[0:1], 0, v[128:129]
	v_writelane_b32 v254, s20, 23
	v_or_b32_e32 v2, s15, v90
	v_lshlrev_b32_e32 v128, 1, v45
	v_lshl_add_u64 v[0:1], v[0:1], 0, s[20:21]
	v_mad_i64_i32 v[2:3], s[10:11], v2, s9, v[62:63]
	v_lshl_add_u64 v[12:13], v[0:1], 0, v[128:129]
	global_load_dwordx4 v[24:27], v[2:3], off
	s_nop 0
	global_load_dwordx4 v[12:15], v[12:13], off offset:512
	v_or_b32_e32 v2, 0x100, v42
	v_lshrrev_b32_e32 v46, 3, v2
	v_lshlrev_b32_e32 v3, 4, v2
	v_xor_b32_e32 v2, 63, v46
	v_cndmask_b32_e64 v91, v2, v46, s[2:3]
	v_or_b32_e32 v2, s15, v91
	v_and_b32_e32 v48, 56, v46
	global_load_dwordx4 v[16:19], v3, s[4:5]
	global_load_dwordx4 v[20:23], v3, s[6:7]
	v_mad_i64_i32 v[2:3], s[4:5], v2, s9, v[62:63]
	v_lshlrev_b32_e32 v64, 1, v48
	v_mov_b32_e32 v65, v129
	v_lshl_add_u64 v[0:1], v[0:1], 0, v[64:65]
	global_load_dwordx4 v[32:35], v[2:3], off
	global_load_dwordx4 v[28:31], v[0:1], off offset:512
	s_movk_i32 s4, 0x80
	v_and_b32_e32 v36, 8, v36
	v_writelane_b32 v254, s21, 24
	s_and_b32 s19, s12, 3
	v_cmp_gt_u32_e64 s[4:5], s4, v42
	v_mov_b32_e32 v0, v129
	v_mov_b32_e32 v1, v129
	v_mov_b32_e32 v2, v129
	v_mov_b32_e32 v3, v129
	v_lshlrev_b32_e32 v47, 6, v42
	v_lshlrev_b32_e32 v36, 1, v36
	s_and_saveexec_b64 s[6:7], s[4:5]
	s_cbranch_execz .LBB0_1375
	s_add_u32 s10, s54, s13
	v_readlane_b32 s20, v254, 23
	s_addc_u32 s11, s55, s17
	v_and_b32_e32 v0, 0x1f80, v47
	v_mov_b32_e32 v1, v129
	v_readlane_b32 s21, v254, 24
	v_lshl_add_u64 v[0:1], s[10:11], 0, v[0:1]
	s_lshl_b32 s10, s19, 5
	s_mov_b32 s11, s21
	v_lshl_add_u64 v[0:1], v[0:1], 0, s[10:11]
	v_mov_b32_e32 v37, v129
	v_lshl_add_u64 v[0:1], v[0:1], 0, v[36:37]
	global_load_dwordx4 v[0:3], v[0:1], off

.LBB0_1377:
	s_or_b64 exec, exec, s[10:11]
	s_and_b64 s[8:9], s[2:3], exec
	s_cselect_b32 s9, s60, s62
	v_readlane_b32 s10, v254, 23
	s_cselect_b32 s8, s61, s63
	v_and_b32_e32 v50, 15, v39
	v_lshrrev_b32_e32 v52, 2, v39
	v_readlane_b32 s11, v254, 24
	s_add_u32 s9, s9, s10
	v_bfe_u32 v37, v39, 4, 2
	v_mul_u32_u24_e32 v51, 0x48, v50
	v_and_b32_e32 v52, 48, v52
	s_addc_u32 s10, s8, 0
	s_lshl_b32 s11, s19, 5
	v_lshl_add_u32 v51, v51, 1, s33
	v_lshlrev_b32_e32 v53, 1, v52
	v_lshlrev_b32_e32 v54, 2, v37
	v_lshlrev_b32_e32 v55, 3, v37
	v_lshlrev_b32_e32 v37, 4, v37
	s_add_u32 s8, s9, s11
	v_add3_u32 v86, v51, v53, v55
	v_or_b32_e32 v53, v52, v50
	v_add_u32_e32 v83, v51, v37
	s_addc_u32 s9, s10, 0
	v_lshlrev_b32_e32 v50, 1, v50
	v_mov_b32_e32 v51, v129
	v_lshl_add_u64 v[60:61], s[8:9], 0, v[50:51]
	v_lshrrev_b32_e32 v51, 1, v42
	v_mul_u32_u24_e32 v51, 48, v51
	v_lshl_add_u32 v49, v49, 1, s33
	v_add3_u32 v96, s33, v51, v36
	v_mul_u32_u24_e32 v36, 0x48, v44
	v_lshl_add_u32 v100, v36, 1, v49
	v_mul_u32_u24_e32 v36, 0x48, v45
	v_lshlrev_b32_e32 v36, 1, v36
	v_lshlrev_b32_e32 v43, 1, v43
	v_mul_u32_u24_e32 v53, 0x48, v53
	v_add3_u32 v99, s33, v36, v43
	v_mul_u32_u24_e32 v36, 0x48, v46
	v_lshlrev_b32_e32 v53, 1, v53
	v_lshl_add_u32 v98, v36, 1, v49
	v_mul_u32_u24_e32 v36, 0x48, v48
	v_add3_u32 v82, s33, v53, v37
	v_or_b32_e32 v37, v54, v52
	v_lshlrev_b32_e32 v36, 1, v36
	v_bitop3_b32 v48, v54, 63, v52 bitop3:0x36
	v_lshl_add_u32 v84, v37, 2, s33
	v_add3_u32 v97, s33, v36, v43
	v_mad_u32_u24 v43, v37, 48, s33
	v_or_b32_e32 v36, 1, v37
	v_mul_i32_i24_e32 v44, 0xffffffd4, v37
	v_or_b32_e32 v45, 2, v37
	v_or_b32_e32 v46, 3, v37
	v_cndmask_b32_e64 v85, v48, v37, s[2:3]
	v_bitop3_b32 v37, v54, 62, v52 bitop3:0x36
	v_cndmask_b32_e64 v81, v37, v36, s[2:3]
	v_bitop3_b32 v36, v54, 61, v52 bitop3:0x36
	v_cndmask_b32_e64 v80, v36, v45, s[2:3]
	v_bitop3_b32 v36, v54, 60, v52 bitop3:0x36
	v_cndmask_b32_e64 v78, v36, v46, s[2:3]
	v_and_b32_e32 v36, 0x1f80, v47
	v_and_b32_e32 v37, 1, v39
	v_or_b32_e32 v36, s13, v36
	v_lshlrev_b32_e32 v37, 4, v37
	v_readlane_b32 s8, v254, 11
	v_or3_b32 v36, v36, s11, v37
	v_mov_b32_e32 v37, s17
	v_readlane_b32 s9, v254, 12
	v_mov_b32_e32 v39, v129
	v_add_u32_e32 v95, s33, v38
	v_lshl_add_u64 v[70:71], s[8:9], 0, v[36:37]
	v_readlane_b32 s8, v254, 13
	v_add_u32_e32 v93, v43, v50
	v_lshl_add_u64 v[38:39], v[40:41], 0, v[38:39]
	v_readlane_b32 s9, v254, 14
	v_lshl_or_b32 v36, v42, 4, s13
	s_lshl_b32 s16, s16, 12
	v_add_u32_e32 v92, 48, v93
	v_add_u32_e32 v89, 0x60, v93
	v_add_u32_e32 v87, 0x90, v93
	v_lshl_add_u64 v[72:73], s[8:9], 0, v[38:39]
	v_lshl_add_u64 v[74:75], s[52:53], 0, v[36:37]
	v_lshl_add_u64 v[76:77], s[56:57], 0, v[36:37]
	s_movk_i32 s17, 0x42
	s_mov_b32 s19, -3
	s_mov_b64 s[8:9], 0
	v_add_u32_e32 v79, v43, v44
	v_mov_b32_e32 v67, v66
	v_mov_b32_e32 v68, v66
	v_mov_b32_e32 v69, v66
	s_add_i32 s10, s19, 3
	s_cmp_gt_u32 s10, 2
	s_mov_b64 s[10:11], -1
	s_cbranch_scc0 .Lscanp_1384
	s_and_b64 s[10:11], s[2:3], exec
	s_cselect_b32 s13, s19, s17
	s_mov_b64 s[10:11], 0

.Lscanp_1386:
	s_lshl_b32 s13, s13, 6
	s_add_i32 s13, s13, s10
	v_add_u32_e32 v214, s13, v88
	v_mov_b64_e32 v[212:213], s[0:1]
	s_movk_i32 s20, 0x600
	v_lshl_add_u64 v[224:225], v[74:75], 0, s[8:9]
	v_mad_i64_i32 v[236:237], s[10:11], v214, s20, v[212:213]
	v_add_co_u32_e32 v212, vcc, 0x2000, v224
	v_lshl_add_u64 v[228:229], v[76:77], 0, s[8:9]
	s_nop 0
	v_addc_co_u32_e32 v213, vcc, 0, v225, vcc
	v_add_co_u32_e32 v216, vcc, 0x2000, v228
	v_add_u32_e32 v220, s13, v90
	s_nop 0
	v_addc_co_u32_e32 v217, vcc, 0, v229, vcc
	v_add_co_u32_e32 v224, vcc, 0x3000, v224
	v_add_u32_e32 v238, s13, v91
	s_nop 0
	v_addc_co_u32_e32 v225, vcc, 0, v225, vcc
	v_add_co_u32_e32 v228, vcc, 0x3000, v228
	v_mov_b32_e32 v65, v129
	v_mad_i64_i32 v[220:221], s[10:11], v220, s20, v[62:63]
	v_lshl_add_u64 v[222:223], v[236:237], 0, v[128:129]
	v_addc_co_u32_e32 v229, vcc, 0, v229, vcc
	v_mad_i64_i32 v[238:239], s[10:11], v238, s20, v[62:63]
	v_lshl_add_u64 v[236:237], v[236:237], 0, v[64:65]
	global_load_dwordx4 v[212:215], v[212:213], off
	s_nop 0
	global_load_dwordx4 v[216:219], v[216:217], off
	s_nop 0
	global_load_dwordx4 v[232:235], v[220:221], off
	s_nop 0
	global_load_dwordx4 v[220:223], v[222:223], off offset:512
	s_nop 0
	global_load_dwordx4 v[224:227], v[224:225], off
	s_nop 0
	global_load_dwordx4 v[228:231], v[228:229], off
	s_nop 0
	global_load_dwordx4 v[240:243], v[238:239], off
	s_nop 0
	global_load_dwordx4 v[236:239], v[236:237], off offset:512
	s_and_saveexec_b64 s[10:11], s[4:5]
	s_cbranch_execz .Lscanp_1388
	v_lshl_add_u64 v[208:209], v[70:71], 0, s[8:9]
	global_load_dwordx4 v[208:211], v[208:209], off
.Lscanp_1388:
	s_or_b64 exec, exec, s[10:11]
	s_and_saveexec_b64 s[10:11], s[6:7]
	s_cbranch_execz .Lscanp_1390
	global_load_dword v244, v[72:73], off
.Lscanp_1390:
	s_or_b64 exec, exec, s[10:11]
	s_add_i32 s17, s17, -1
	s_add_i32 s19, s19, 1
	s_add_u32 s8, s8, 0x2000
	s_addc_u32 s9, s9, 0
	v_lshl_add_u64 v[72:73], v[72:73], 0, s[88:89]
	s_mov_b32 s24, s13
.LBB0_1378:
	s_barrier
	s_waitcnt vmcnt(15)
	ds_write_b128 v100, v[4:7]
	s_waitcnt vmcnt(14)
	ds_write_b128 v100, v[8:11] offset:9216
	s_waitcnt vmcnt(13)
	ds_write_b128 v100, v[24:27] offset:18432
	s_waitcnt vmcnt(12)
	ds_write_b16 v99, v12 offset:27648
	ds_write_b16_d16_hi v99, v12 offset:27792
	ds_write_b16 v99, v13 offset:27936
	ds_write_b16_d16_hi v99, v13 offset:28080
	ds_write_b16 v99, v14 offset:28224
	ds_write_b16_d16_hi v99, v14 offset:28368
	ds_write_b16 v99, v15 offset:28512
	ds_write_b16_d16_hi v99, v15 offset:28656
	s_waitcnt vmcnt(11)
	ds_write_b128 v98, v[16:19]
	s_waitcnt vmcnt(10)
	ds_write_b128 v98, v[20:23] offset:9216
	s_waitcnt vmcnt(9)
	ds_write_b128 v98, v[32:35] offset:18432
	s_waitcnt vmcnt(8)
	ds_write_b16 v97, v28 offset:27648
	ds_write_b16_d16_hi v97, v28 offset:27792
	ds_write_b16 v97, v29 offset:27936
	ds_write_b16_d16_hi v97, v29 offset:28080
	ds_write_b16 v97, v30 offset:28224
	ds_write_b16_d16_hi v97, v30 offset:28368
	ds_write_b16 v97, v31 offset:28512
	ds_write_b16_d16_hi v97, v31 offset:28656
	s_and_saveexec_b64 s[10:11], s[4:5]
	ds_write_b128 v96, v[0:3] offset:36864
	s_or_b64 exec, exec, s[10:11]
	s_and_saveexec_b64 s[10:11], s[6:7]
	ds_write_b32 v95, v94 offset:46848
	s_or_b64 exec, exec, s[10:11]
	v_cvt_pk_bf16_f32 v4, v66, v67
	v_cvt_pk_bf16_f32 v5, v68, v69
	ds_write_b64 v86, v[4:5] offset:39936
	s_waitcnt lgkmcnt(0)
	s_barrier
	s_cmp_gt_i32 s19, 63
	s_cbranch_scc1 .Lscana_skip
	s_add_i32 s10, s19, 3
	s_cmp_gt_u32 s10, 2
	s_mov_b64 s[10:11], -1
	s_cbranch_scc0 .Lscana_1384
	s_and_b64 s[10:11], s[2:3], exec
	s_cselect_b32 s13, s19, s17
	s_mov_b64 s[10:11], 0

.Lscana_skip:
	v_mov_b32_e32 v36, s33
	ds_read_b32 v101, v36 offset:47100
	ds_read_b128 v[36:39], v82
	ds_read_b128 v[40:43], v83 offset:39936
	v_add_u32_e32 v65, 0xb704, v79
	s_add_i32 s17, s17, -1
	s_add_i32 s19, s19, 1
	s_add_u32 s8, s8, 0x2000
	s_waitcnt lgkmcnt(0)
	v_mfma_f32_16x16x32_bf16 v[36:39], v[36:39], v[40:43], 0
	ds_read_b128 v[40:43], v82 offset:64
	ds_read_b128 v[44:47], v83 offset:40000
	s_addc_u32 s9, s9, 0
	v_lshl_add_u64 v[72:73], v[72:73], 0, s[88:89]
	s_cmp_lg_u32 s8, 0x8a000
	s_waitcnt lgkmcnt(0)
	v_mfma_f32_16x16x32_bf16 v[36:39], v[40:43], v[44:47], v[36:39]
	ds_read_b32 v40, v84 offset:46848
	ds_read2_b32 v[42:43], v65 offset1:1
	s_waitcnt lgkmcnt(1)
	v_sub_f32_e32 v40, v101, v40
	s_waitcnt lgkmcnt(0)
	v_sub_f32_e32 v41, v101, v42
	ds_read_u16 v42, v93 offset:36864
	ds_read_u16 v44, v92 offset:36864
	v_mul_f32_e32 v40, 0x3fb8aa3b, v40
	v_mul_f32_e32 v41, 0x3fb8aa3b, v41
	v_exp_f32_e32 v40, v40
	v_exp_f32_e32 v41, v41
	s_waitcnt lgkmcnt(0)
	v_lshlrev_b32_e32 v45, 16, v44
	v_lshlrev_b32_e32 v44, 16, v42
	v_sub_f32_e32 v42, v101, v43
	ds_read_b32 v43, v79 offset:46860
	v_pk_add_f32 v[36:37], v[44:45], v[36:37] neg_lo:[0,1] neg_hi:[0,1]
	ds_read_u16 v44, v89 offset:36864
	ds_read_u16 v45, v87 offset:36864
	v_mul_f32_e32 v42, 0x3fb8aa3b, v42
	v_exp_f32_e32 v42, v42
	s_waitcnt lgkmcnt(2)
	v_sub_f32_e32 v43, v101, v43
	v_mul_f32_e32 v43, 0x3fb8aa3b, v43
	v_exp_f32_e32 v43, v43
	s_waitcnt lgkmcnt(0)
	v_lshlrev_b32_e32 v45, 16, v45
	v_lshlrev_b32_e32 v44, 16, v44
	v_pk_add_f32 v[38:39], v[44:45], v[38:39] neg_lo:[0,1] neg_hi:[0,1]
	v_pk_mul_f32 v[40:41], v[36:37], v[40:41]
	v_pk_mul_f32 v[42:43], v[38:39], v[42:43]
	v_cvt_pk_bf16_f32 v36, v36, v37
	v_cvt_pk_bf16_f32 v37, v38, v39
	ds_write_b64 v86, v[36:37] offset:42240
	v_cvt_pk_bf16_f32 v36, v40, v41
	v_cvt_pk_bf16_f32 v37, v42, v43
	ds_write_b64 v86, v[36:37] offset:44544
	s_waitcnt lgkmcnt(0)
	s_barrier
	ds_read_b128 v[36:39], v83 offset:39936
	ds_read_b128 v[40:43], v82 offset:18432
	s_waitcnt lgkmcnt(0)
	v_mfma_f32_16x16x32_bf16 v[44:47], v[40:43], v[36:39], 0
	ds_read_b128 v[36:39], v82 offset:9216
	ds_read_b128 v[40:43], v83 offset:42240
	s_waitcnt lgkmcnt(0)
	v_mfma_f32_16x16x32_bf16 v[48:51], v[36:39], v[40:43], 0
	ds_read_b128 v[36:39], v82 offset:27648
	ds_read_b128 v[40:43], v83 offset:44544
	ds_read_b128 v[52:55], v83 offset:40000
	ds_read_b128 v[56:59], v82 offset:18496
	s_waitcnt lgkmcnt(0)
	v_mfma_f32_16x16x32_bf16 v[44:47], v[56:59], v[52:55], v[44:47]
	ds_read_b128 v[52:55], v82 offset:9280
	ds_read_b128 v[56:59], v83 offset:42304
	s_waitcnt lgkmcnt(0)
	v_mfma_f32_16x16x32_bf16 v[56:59], v[52:55], v[56:59], v[48:51]
	s_nop 2
	ds_read_b128 v[48:51], v82 offset:27712
	ds_read_b128 v[52:55], v83 offset:44608
	ds_read_b32 v102, v84 offset:46848
	s_waitcnt lgkmcnt(0)
	v_mul_f32_e32 v102, 0x3fb8aa3b, v102
	v_exp_f32_e32 v102, v102
	v_mfma_f32_16x16x32_bf16 v[36:39], v[36:39], v[40:43], 0
	v_mul_f32_e32 v40, 0x3fb8aa3b, v101
	v_exp_f32_e32 v40, v40
	v_fma_f32 v44, v44, v102, v56
	v_add_u32_e32 v102, s15, v85
	v_ashrrev_i32_e32 v103, 31, v102
	v_bfe_u32 v56, v44, 16, 1
	v_lshlrev_b64 v[102:103], 9, v[102:103]
	v_add3_u32 v44, v44, v56, s42
	v_lshl_add_u64 v[102:103], v[60:61], 0, v[102:103]
	global_store_short_d16_hi v[102:103], v44, off
	ds_read2_b32 v[102:103], v65 offset1:1
	v_mfma_f32_16x16x32_bf16 v[36:39], v[48:51], v[52:55], v[36:39]
	s_waitcnt lgkmcnt(0)
	v_mul_f32_e32 v44, 0x3fb8aa3b, v102
	v_exp_f32_e32 v44, v44
	s_nop 4
	v_pk_fma_f32 v[68:69], v[68:69], v[40:41], v[38:39] op_sel_hi:[1,0,1]
	v_pk_fma_f32 v[66:67], v[66:67], v[40:41], v[36:37] op_sel_hi:[1,0,1]
	v_fma_f32 v44, v45, v44, v57
	v_bfe_u32 v45, v44, 16, 1
	v_add3_u32 v56, v44, v45, s42
	v_add_u32_e32 v44, s15, v81
	v_ashrrev_i32_e32 v45, 31, v44
	v_lshlrev_b64 v[44:45], 9, v[44:45]
	v_lshl_add_u64 v[44:45], v[60:61], 0, v[44:45]
	global_store_short_d16_hi v[44:45], v56, off
	v_mul_f32_e32 v44, 0x3fb8aa3b, v103
	v_exp_f32_e32 v44, v44
	s_nop 0
	v_fma_f32 v44, v46, v44, v58
	v_bfe_u32 v45, v44, 16, 1
	v_add3_u32 v46, v44, v45, s42
	v_add_u32_e32 v44, s15, v80
	v_ashrrev_i32_e32 v45, 31, v44
	v_lshlrev_b64 v[44:45], 9, v[44:45]
	v_lshl_add_u64 v[44:45], v[60:61], 0, v[44:45]
	global_store_short_d16_hi v[44:45], v46, off
	ds_read_b32 v44, v79 offset:46860
	s_waitcnt lgkmcnt(0)
	v_mul_f32_e32 v44, 0x3fb8aa3b, v44
	v_exp_f32_e32 v44, v44
	s_nop 0
	v_fmac_f32_e32 v59, v47, v44
	v_bfe_u32 v44, v59, 16, 1
	v_add3_u32 v46, v59, v44, s42
	v_add_u32_e32 v44, s15, v78
	v_ashrrev_i32_e32 v45, 31, v44
	v_lshlrev_b64 v[44:45], 9, v[44:45]
	v_lshl_add_u64 v[44:45], v[60:61], 0, v[44:45]
	global_store_short_d16_hi v[44:45], v46, off
	s_mov_b32 s15, s24
	s_mov_b32 s24, s13
	s_barrier
	s_cmp_lt_i32 s19, 65
	s_cbranch_scc1 .Lscanb_nl
	s_waitcnt vmcnt(0)
.Lscanb_nl:
	s_waitcnt vmcnt(15)
	ds_write_b128 v100, v[212:215]
	s_waitcnt vmcnt(14)
	ds_write_b128 v100, v[216:219] offset:9216
	s_waitcnt vmcnt(13)
	ds_write_b128 v100, v[232:235] offset:18432
	s_waitcnt vmcnt(12)
	ds_write_b16 v99, v220 offset:27648
	ds_write_b16_d16_hi v99, v220 offset:27792
	ds_write_b16 v99, v221 offset:27936
	ds_write_b16_d16_hi v99, v221 offset:28080
	ds_write_b16 v99, v222 offset:28224
	ds_write_b16_d16_hi v99, v222 offset:28368
	ds_write_b16 v99, v223 offset:28512
	ds_write_b16_d16_hi v99, v223 offset:28656
	s_waitcnt vmcnt(11)
	ds_write_b128 v98, v[224:227]
	s_waitcnt vmcnt(10)
	ds_write_b128 v98, v[228:231] offset:9216
	s_waitcnt vmcnt(9)
	ds_write_b128 v98, v[240:243] offset:18432
	s_waitcnt vmcnt(8)
	ds_write_b16 v97, v236 offset:27648
	ds_write_b16_d16_hi v97, v236 offset:27792
	ds_write_b16 v97, v237 offset:27936
	ds_write_b16_d16_hi v97, v237 offset:28080
	ds_write_b16 v97, v238 offset:28224
	ds_write_b16_d16_hi v97, v238 offset:28368
	ds_write_b16 v97, v239 offset:28512
	ds_write_b16_d16_hi v97, v239 offset:28656
	s_and_saveexec_b64 s[10:11], s[4:5]
	ds_write_b128 v96, v[208:211] offset:36864
	s_or_b64 exec, exec, s[10:11]
	s_and_saveexec_b64 s[10:11], s[6:7]
	ds_write_b32 v95, v244 offset:46848
	s_or_b64 exec, exec, s[10:11]
	v_cvt_pk_bf16_f32 v212, v66, v67
	v_cvt_pk_bf16_f32 v213, v68, v69
	ds_write_b64 v86, v[212:213] offset:39936
	s_waitcnt lgkmcnt(0)
	s_barrier
	s_cmp_gt_i32 s19, 63
	s_cbranch_scc1 .Lscanb_skip
	s_add_i32 s10, s19, 3
	s_cmp_gt_u32 s10, 2
	s_mov_b64 s[10:11], -1
	s_cbranch_scc0 .Lscanb_1384
	s_and_b64 s[10:11], s[2:3], exec
	s_cselect_b32 s13, s19, s17
	s_mov_b64 s[10:11], 0

.Lscanb_skip:
	v_mov_b32_e32 v36, s33
	ds_read_b32 v101, v36 offset:47100
	ds_read_b128 v[36:39], v82
	ds_read_b128 v[40:43], v83 offset:39936
	v_add_u32_e32 v65, 0xb704, v79
	s_add_i32 s17, s17, -1
	s_add_i32 s19, s19, 1
	s_add_u32 s8, s8, 0x2000
	s_waitcnt lgkmcnt(0)
	v_mfma_f32_16x16x32_bf16 v[36:39], v[36:39], v[40:43], 0
	ds_read_b128 v[40:43], v82 offset:64
	ds_read_b128 v[44:47], v83 offset:40000
	s_addc_u32 s9, s9, 0
	v_lshl_add_u64 v[72:73], v[72:73], 0, s[88:89]
	s_cmp_lg_u32 s8, 0x8a000
	s_waitcnt lgkmcnt(0)
	v_mfma_f32_16x16x32_bf16 v[36:39], v[40:43], v[44:47], v[36:39]
	ds_read_b32 v40, v84 offset:46848
	ds_read2_b32 v[42:43], v65 offset1:1
	s_waitcnt lgkmcnt(1)
	v_sub_f32_e32 v40, v101, v40
	s_waitcnt lgkmcnt(0)
	v_sub_f32_e32 v41, v101, v42
	ds_read_u16 v42, v93 offset:36864
	ds_read_u16 v44, v92 offset:36864
	v_mul_f32_e32 v40, 0x3fb8aa3b, v40
	v_mul_f32_e32 v41, 0x3fb8aa3b, v41
	v_exp_f32_e32 v40, v40
	v_exp_f32_e32 v41, v41
	s_waitcnt lgkmcnt(0)
	v_lshlrev_b32_e32 v45, 16, v44
	v_lshlrev_b32_e32 v44, 16, v42
	v_sub_f32_e32 v42, v101, v43
	ds_read_b32 v43, v79 offset:46860
	v_pk_add_f32 v[36:37], v[44:45], v[36:37] neg_lo:[0,1] neg_hi:[0,1]
	ds_read_u16 v44, v89 offset:36864
	ds_read_u16 v45, v87 offset:36864
	v_mul_f32_e32 v42, 0x3fb8aa3b, v42
	v_exp_f32_e32 v42, v42
	s_waitcnt lgkmcnt(2)
	v_sub_f32_e32 v43, v101, v43
	v_mul_f32_e32 v43, 0x3fb8aa3b, v43
	v_exp_f32_e32 v43, v43
	s_waitcnt lgkmcnt(0)
	v_lshlrev_b32_e32 v45, 16, v45
	v_lshlrev_b32_e32 v44, 16, v44
	v_pk_add_f32 v[38:39], v[44:45], v[38:39] neg_lo:[0,1] neg_hi:[0,1]
	v_pk_mul_f32 v[40:41], v[36:37], v[40:41]
	v_pk_mul_f32 v[42:43], v[38:39], v[42:43]
	v_cvt_pk_bf16_f32 v36, v36, v37
	v_cvt_pk_bf16_f32 v37, v38, v39
	ds_write_b64 v86, v[36:37] offset:42240
	v_cvt_pk_bf16_f32 v36, v40, v41
	v_cvt_pk_bf16_f32 v37, v42, v43
	ds_write_b64 v86, v[36:37] offset:44544
	s_waitcnt lgkmcnt(0)
	s_barrier
	ds_read_b128 v[36:39], v83 offset:39936
	ds_read_b128 v[40:43], v82 offset:18432
	s_waitcnt lgkmcnt(0)
	v_mfma_f32_16x16x32_bf16 v[44:47], v[40:43], v[36:39], 0
	ds_read_b128 v[36:39], v82 offset:9216
	ds_read_b128 v[40:43], v83 offset:42240
	s_waitcnt lgkmcnt(0)
	v_mfma_f32_16x16x32_bf16 v[48:51], v[36:39], v[40:43], 0
	ds_read_b128 v[36:39], v82 offset:27648
	ds_read_b128 v[40:43], v83 offset:44544
	ds_read_b128 v[52:55], v83 offset:40000
	ds_read_b128 v[56:59], v82 offset:18496
	s_waitcnt lgkmcnt(0)
	v_mfma_f32_16x16x32_bf16 v[44:47], v[56:59], v[52:55], v[44:47]
	ds_read_b128 v[52:55], v82 offset:9280
	ds_read_b128 v[56:59], v83 offset:42304
	s_waitcnt lgkmcnt(0)
	v_mfma_f32_16x16x32_bf16 v[56:59], v[52:55], v[56:59], v[48:51]
	s_nop 2
	ds_read_b128 v[48:51], v82 offset:27712
	ds_read_b128 v[52:55], v83 offset:44608
	ds_read_b32 v102, v84 offset:46848
	s_waitcnt lgkmcnt(0)
	v_mul_f32_e32 v102, 0x3fb8aa3b, v102
	v_exp_f32_e32 v102, v102
	v_mfma_f32_16x16x32_bf16 v[36:39], v[36:39], v[40:43], 0
	v_mul_f32_e32 v40, 0x3fb8aa3b, v101
	v_exp_f32_e32 v40, v40
	v_fma_f32 v44, v44, v102, v56
	v_add_u32_e32 v102, s15, v85
	v_ashrrev_i32_e32 v103, 31, v102
	v_bfe_u32 v56, v44, 16, 1
	v_lshlrev_b64 v[102:103], 9, v[102:103]
	v_add3_u32 v44, v44, v56, s42
	v_lshl_add_u64 v[102:103], v[60:61], 0, v[102:103]
	global_store_short_d16_hi v[102:103], v44, off
	ds_read2_b32 v[102:103], v65 offset1:1
	v_mfma_f32_16x16x32_bf16 v[36:39], v[48:51], v[52:55], v[36:39]
	s_waitcnt lgkmcnt(0)
	v_mul_f32_e32 v44, 0x3fb8aa3b, v102
	v_exp_f32_e32 v44, v44
	s_nop 4
	v_pk_fma_f32 v[68:69], v[68:69], v[40:41], v[38:39] op_sel_hi:[1,0,1]
	v_pk_fma_f32 v[66:67], v[66:67], v[40:41], v[36:37] op_sel_hi:[1,0,1]
	v_fma_f32 v44, v45, v44, v57
	v_bfe_u32 v45, v44, 16, 1
	v_add3_u32 v56, v44, v45, s42
	v_add_u32_e32 v44, s15, v81
	v_ashrrev_i32_e32 v45, 31, v44
	v_lshlrev_b64 v[44:45], 9, v[44:45]
	v_lshl_add_u64 v[44:45], v[60:61], 0, v[44:45]
	global_store_short_d16_hi v[44:45], v56, off
	v_mul_f32_e32 v44, 0x3fb8aa3b, v103
	v_exp_f32_e32 v44, v44
	s_nop 0
	v_fma_f32 v44, v46, v44, v58
	v_bfe_u32 v45, v44, 16, 1
	v_add3_u32 v46, v44, v45, s42
	v_add_u32_e32 v44, s15, v80
	v_ashrrev_i32_e32 v45, 31, v44
	v_lshlrev_b64 v[44:45], 9, v[44:45]
	v_lshl_add_u64 v[44:45], v[60:61], 0, v[44:45]
	global_store_short_d16_hi v[44:45], v46, off
	ds_read_b32 v44, v79 offset:46860
	s_waitcnt lgkmcnt(0)
	v_mul_f32_e32 v44, 0x3fb8aa3b, v44
	v_exp_f32_e32 v44, v44
	s_nop 0
	v_fmac_f32_e32 v59, v47, v44
	v_bfe_u32 v44, v59, 16, 1
	v_add3_u32 v46, v59, v44, s42
	v_add_u32_e32 v44, s15, v78
	v_ashrrev_i32_e32 v45, 31, v44
	v_lshlrev_b64 v[44:45], 9, v[44:45]
	v_lshl_add_u64 v[44:45], v[60:61], 0, v[44:45]
	global_store_short_d16_hi v[44:45], v46, off
	s_mov_b32 s15, s24
	s_mov_b32 s24, s13
	s_cbranch_scc0 .Lscan_done
	s_branch .LBB0_1378
.Lscan_done:
	v_readlane_b32 s0, v252, 26
	s_nop 1
	s_add_i32 s12, s0, s12
	s_branch .LBB0_1372
